# attention C: K/V tile loads use SGPR base plus constant lane offsets instead of per-step 64-bit VALU address arithmetic
# speedup vs baseline: 1.0070x; 1.0023x over previous
.LBB0_739:
	s_lshl_b32 s8, s56, 5
	s_add_i32 s8, s8, s55
	v_readlane_b32 s18, v254, 6
	s_or_b32 s8, s8, s54
	v_readlane_b32 s19, v254, 7
	s_and_b64 s[18:19], s[18:19], exec
	s_cselect_b32 s58, s8, s45
	s_ashr_i32 s18, s58, 6
	s_lshl_b32 s8, s58, 7
	s_ashr_i32 s19, s18, 31
	s_and_b32 s8, s8, 0x780
	s_lshl_b64 s[40:41], s[18:19], 20
	s_lshl_b64 s[42:43], s[18:19], 21
	s_add_u32 s17, s12, s42
	s_addc_u32 s18, s13, s43
	s_lshl_b32 s19, s58, 3
	s_and_b32 s57, s19, 0x180
	s_lshl_b32 s22, s57, 1
	s_add_u32 s17, s17, s22
	s_addc_u32 s19, s18, 0
	s_add_u32 s18, s17, s38
	s_addc_u32 s19, s19, s39
	s_add_u32 s17, s48, s42
	s_addc_u32 s21, s49, s43
	s_add_u32 s20, s17, s22
	s_addc_u32 s21, s21, 0
	s_add_u32 s17, s50, s42
	s_addc_u32 s23, s51, s43
	s_add_u32 s22, s17, s22
	s_addc_u32 s23, s23, 0
	v_lshl_add_u64 v[0:1], s[20:21], 0, v[216:217]
	v_lshl_add_u64 v[2:3], s[20:21], 0, v[220:221]
	v_lshl_add_u64 v[8:9], s[22:23], 0, v[216:217]
	v_lshl_add_u64 v[10:11], s[22:23], 0, v[220:221]
	v_lshl_add_u64 v[0:1], v[0:1], 0, v[218:219]
	v_lshl_add_u64 v[4:5], v[2:3], 0, v[222:223]
	v_lshl_add_u64 v[8:9], v[8:9], 0, v[218:219]
	v_lshl_add_u64 v[12:13], v[10:11], 0, v[222:223]
	global_load_dwordx4 v[0:3], v[0:1], off
	s_nop 0
	global_load_dwordx4 v[4:7], v[4:5], off
	s_nop 0
	global_load_dwordx4 v[8:11], v[8:9], off
	s_nop 0
	global_load_dwordx4 v[12:15], v[12:13], off
	v_or_b32_e32 v16, s8, v233
	v_lshlrev_b32_e32 v192, 10, v16
	v_lshl_add_u64 v[16:17], s[18:19], 0, v[192:193]
	v_mov_b32_e32 v215, v193
	v_lshl_add_u64 v[16:17], v[16:17], 0, v[214:215]
	global_load_dwordx4 v[160:163], v[16:17], off
	global_load_dwordx4 v[164:167], v[16:17], off offset:32
	global_load_dwordx4 v[168:171], v[16:17], off offset:64
	global_load_dwordx4 v[172:175], v[16:17], off offset:96
	v_lshl_add_u64 v[16:17], s[20:21], 0, v[196:197]
	v_lshl_add_u64 v[18:19], s[20:21], 0, v[198:199]
	v_lshl_add_u64 v[16:17], v[16:17], 0, v[218:219]
	v_lshl_add_u64 v[18:19], v[18:19], 0, v[222:223]
	global_load_dwordx4 v[176:179], v[16:17], off
	global_load_dwordx4 v[180:183], v[18:19], off
	v_add_u32_e32 v192, v202, v234
	v_add_u32_e32 v215, v204, v235
	v_add_u32_e32 v243, v206, v234
	v_add_u32_e32 v244, v208, v235
	s_mov_b32 s17, s16
	s_mov_b32 s18, s16
	s_mov_b32 s19, s16
	s_mov_b32 s20, s16
	s_mov_b32 s21, s16
	s_mov_b32 s22, s16
	s_mov_b32 s23, s16
	s_mov_b32 s24, s16
	s_mov_b32 s25, s16
	s_mov_b32 s26, s16
	s_mov_b32 s27, s16
	s_mov_b32 s28, s16
	s_mov_b32 s29, s16
	s_mov_b32 s30, s16
	s_mov_b32 s31, s16
	v_mov_b32_e32 v246, 0
	v_mov_b32_e32 v245, 0xf149f2ca
	s_waitcnt vmcnt(9)
	ds_write_b128 v192, v[0:3]
	s_waitcnt vmcnt(8)
	ds_write_b128 v215, v[4:7]
	s_waitcnt vmcnt(7)
	ds_write_b128 v243, v[8:11] offset:34816
	s_waitcnt vmcnt(6)
	ds_write_b128 v244, v[12:15] offset:34816
	s_waitcnt lgkmcnt(0)
	s_barrier
	ds_read_b128 v[0:3], v240
	ds_read_b128 v[4:7], v240 offset:32
	s_waitcnt vmcnt(5) lgkmcnt(1)
	v_mfma_f32_32x32x16_bf16 v[80:95], v[0:3], v[160:163], 0
	ds_read_b128 v[0:3], v240 offset:8704
	ds_read_b128 v[8:11], v240 offset:8736
	s_waitcnt lgkmcnt(1)
	v_mfma_f32_32x32x16_bf16 v[64:79], v[0:3], v[160:163], 0
	ds_read_b128 v[0:3], v240 offset:64
	s_waitcnt vmcnt(4)
	v_mfma_f32_32x32x16_bf16 v[80:95], v[4:7], v[164:167], v[80:95]
	ds_read_b128 v[4:7], v240 offset:8768
	ds_read_b128 v[16:19], v240 offset:96
	ds_read_b128 v[20:23], v240 offset:8800
	s_waitcnt vmcnt(1)
	ds_write_b128 v241, v[176:179] offset:17408
	s_waitcnt vmcnt(0)
	ds_write_b128 v242, v[180:183] offset:17408
	s_waitcnt lgkmcnt(0)
	s_barrier
	v_mfma_f32_32x32x16_bf16 v[64:79], v[8:11], v[164:167], v[64:79]
	v_mfma_f32_32x32x16_bf16 v[80:95], v[0:3], v[168:171], v[80:95]
	v_mfma_f32_32x32x16_bf16 v[64:79], v[4:7], v[168:171], v[64:79]
	v_mov_b64_e32 v[0:1], s[16:17]
	v_mov_b64_e32 v[2:3], s[18:19]
	v_mov_b64_e32 v[4:5], s[20:21]
	v_mov_b64_e32 v[6:7], s[22:23]
	v_mov_b64_e32 v[8:9], s[24:25]
	v_mov_b64_e32 v[10:11], s[26:27]
	v_mov_b64_e32 v[12:13], s[28:29]
	v_mfma_f32_32x32x16_bf16 v[80:95], v[16:19], v[172:175], v[80:95]
	v_mov_b64_e32 v[14:15], s[30:31]
	s_lshl_b32 s17, s58, 4
	s_and_b32 s17, s17, 0x300
	s_or_b32 s42, s42, s17
	v_mov_b64_e32 v[46:47], v[14:15]
	v_mov_b64_e32 v[62:63], v[14:15]
	v_lshl_add_u64 v[224:225], v[210:211], 0, s[42:43]
	v_mfma_f32_32x32x16_bf16 v[64:79], v[20:23], v[172:175], v[64:79]
	v_mov_b64_e32 v[30:31], v[14:15]
	v_lshl_add_u64 v[226:227], v[212:213], 0, s[42:43]
	s_mov_b64 s[18:19], 0
	v_mov_b64_e32 v[28:29], v[12:13]
	v_mov_b64_e32 v[26:27], v[10:11]
	v_mov_b64_e32 v[24:25], v[8:9]
	v_mov_b64_e32 v[22:23], v[6:7]
	v_mov_b64_e32 v[20:21], v[4:5]
	v_mov_b64_e32 v[18:19], v[2:3]
	v_mov_b64_e32 v[16:17], v[0:1]
	v_mov_b64_e32 v[44:45], v[12:13]
	v_mov_b64_e32 v[42:43], v[10:11]
	v_mov_b64_e32 v[40:41], v[8:9]
	v_mov_b64_e32 v[38:39], v[6:7]
	v_mov_b64_e32 v[36:37], v[4:5]
	v_mov_b64_e32 v[34:35], v[2:3]
	v_mov_b64_e32 v[32:33], v[0:1]
	v_mov_b64_e32 v[60:61], v[12:13]
	v_mov_b64_e32 v[58:59], v[10:11]
	v_mov_b64_e32 v[56:57], v[8:9]
	v_mov_b64_e32 v[54:55], v[6:7]
	v_mov_b64_e32 v[52:53], v[4:5]
	v_mov_b64_e32 v[50:51], v[2:3]
	v_mov_b64_e32 v[48:49], v[0:1]
	v_readfirstlane_b32 s98, v226
	v_readfirstlane_b32 s99, v227
	s_nop 3
	v_subrev_u32_e32 v247, s98, v226
	v_add_u32_e32 v252, 0x8000, v247
	v_add_u32_e32 v253, 0x10000, v247
	v_add_u32_e32 v245, 0x18000, v247
	s_add_u32 s100, s98, 0xbf10000
	s_addc_u32 s101, s99, 0
	s_add_u32 s98, s98, 0xaf20000
	s_addc_u32 s99, s99, 0
	s_mov_b32 s17, 0
.LBB0_740:
	s_cmp_lg_u32 s18, 0x1e0000
	s_cselect_b64 s[20:21], -1, 0
	s_cmp_eq_u32 s18, 0x1e0000
	s_cbranch_scc1 .LBB0_742
	global_load_dwordx4 v[176:179], v247, s[98:99]
	global_load_dwordx4 v[180:183], v252, s[98:99]
.LBB0_742:
	ds_read_b128 v[96:99], v240 offset:17408
	ds_read_b128 v[128:131], v240 offset:17440
	s_waitcnt lgkmcnt(1)
	v_mfma_f32_32x32x16_bf16 v[112:127], v[96:99], v[160:163], 0
	ds_read_b128 v[96:99], v240 offset:26112
	ds_read_b128 v[132:135], v240 offset:26144
	global_load_dwordx4 v[184:187], v247, s[100:101]
	global_load_dwordx4 v[188:191], v252, s[100:101]
	s_waitcnt lgkmcnt(1)
	v_mfma_f32_32x32x16_bf16 v[96:111], v[96:99], v[160:163], 0
	v_mfma_f32_32x32x16_bf16 v[112:127], v[128:131], v[164:167], v[112:127]
	ds_read_b128 v[128:131], v240 offset:17472
	ds_read_b128 v[136:139], v240 offset:17504
	s_waitcnt lgkmcnt(2)
	v_mfma_f32_32x32x16_bf16 v[96:111], v[132:135], v[164:167], v[96:111]
	ds_read_b128 v[132:135], v240 offset:26176
	ds_read_b128 v[140:143], v240 offset:26208
	s_waitcnt lgkmcnt(3)
	v_mfma_f32_32x32x16_bf16 v[112:127], v[128:131], v[168:171], v[112:127]
	s_waitcnt lgkmcnt(1)
	v_mfma_f32_32x32x16_bf16 v[96:111], v[132:135], v[168:171], v[96:111]
	v_mfma_f32_32x32x16_bf16 v[112:127], v[136:139], v[172:175], v[112:127]
	s_waitcnt lgkmcnt(0)
	v_mfma_f32_32x32x16_bf16 v[96:111], v[140:143], v[172:175], v[96:111]

.LBB0_746:
	s_cmp_lt_u32 s17, 29
	s_cselect_b64 s[20:21], -1, 0
	s_cmp_gt_u32 s17, 28
	s_waitcnt vmcnt(1)
	ds_write_b128 v238, v[184:187] offset:55296
	s_waitcnt vmcnt(0)
	ds_write_b128 v239, v[188:191] offset:55296
	s_waitcnt lgkmcnt(0)
	s_barrier
	s_cbranch_scc1 .LBB0_748
	global_load_dwordx4 v[176:179], v253, s[98:99]
	global_load_dwordx4 v[180:183], v245, s[98:99]
.LBB0_748:
	s_or_b32 s24, s17, 1
	s_cmp_lt_u32 s24, 31
	s_cselect_b64 s[22:23], -1, 0
	s_cmp_gt_u32 s24, 30
	s_cbranch_scc1 .LBB0_750
	ds_read_b128 v[64:67], v240
	ds_read_b128 v[184:187], v240 offset:32
	s_waitcnt lgkmcnt(1)
	v_mfma_f32_32x32x16_bf16 v[80:95], v[64:67], v[160:163], 0
	ds_read_b128 v[64:67], v240 offset:8704
	ds_read_b128 v[188:191], v240 offset:8736
	s_waitcnt lgkmcnt(1)
	v_mfma_f32_32x32x16_bf16 v[64:79], v[64:67], v[160:163], 0
	v_mfma_f32_32x32x16_bf16 v[80:95], v[184:187], v[164:167], v[80:95]
	s_waitcnt lgkmcnt(0)
	v_mfma_f32_32x32x16_bf16 v[64:79], v[188:191], v[164:167], v[64:79]
	ds_read_b128 v[184:187], v240 offset:64
	ds_read_b128 v[188:191], v240 offset:96
	ds_read_b128 v[248:251], v240 offset:8800
	s_waitcnt lgkmcnt(2)
	v_mfma_f32_32x32x16_bf16 v[80:95], v[184:187], v[168:171], v[80:95]
	ds_read_b128 v[184:187], v240 offset:8768
	s_waitcnt lgkmcnt(0)
	v_mfma_f32_32x32x16_bf16 v[64:79], v[184:187], v[168:171], v[64:79]
	v_mfma_f32_32x32x16_bf16 v[80:95], v[188:191], v[172:175], v[80:95]
	global_load_dwordx4 v[184:187], v253, s[100:101]
	global_load_dwordx4 v[188:191], v245, s[100:101]
	v_mfma_f32_32x32x16_bf16 v[64:79], v[248:251], v[172:175], v[64:79]
	s_branch .LBB0_751

.LBB0_757:
	v_pk_add_f32 v[96:97], v[98:99], v[96:97]
	v_pk_add_f32 v[112:113], v[114:115], v[112:113]
	v_pk_add_f32 v[96:97], v[100:101], v[96:97]
	v_pk_add_f32 v[112:113], v[116:117], v[112:113]
	v_pk_add_f32 v[96:97], v[102:103], v[96:97]
	v_pk_add_f32 v[112:113], v[118:119], v[112:113]
	v_pk_add_f32 v[96:97], v[104:105], v[96:97]
	v_pk_add_f32 v[112:113], v[120:121], v[112:113]
	v_pk_add_f32 v[96:97], v[106:107], v[96:97]
	v_pk_add_f32 v[112:113], v[122:123], v[112:113]
	v_pk_add_f32 v[96:97], v[108:109], v[96:97]
	v_pk_add_f32 v[112:113], v[124:125], v[112:113]
	v_pk_add_f32 v[96:97], v[126:127], v[96:97]
	v_pk_add_f32 v[96:97], v[112:113], v[96:97]
	v_add_f32_e32 v96, v96, v97
	v_add_f32_e32 v96, v129, v96
	s_add_u32 s18, s18, 0x20000
	v_add_f32_e32 v96, v130, v96
	s_addc_u32 s19, s19, 0
	s_add_i32 s20, s17, 2
	v_add_f32_e32 v246, v128, v96
	s_cmp_lt_u32 s17, 29
	s_waitcnt lgkmcnt(0)
	s_barrier
	s_cbranch_scc0 .LBB0_759
	s_add_u32 s98, s98, 0x20000
	s_addc_u32 s99, s99, 0
	s_add_u32 s100, s100, 0x20000
	s_addc_u32 s101, s101, 0
	s_mov_b32 s17, s20
	s_branch .LBB0_740

.LBB0_2799:
	s_lshl_b32 s8, s56, 5
	s_add_i32 s8, s8, s55
	v_readlane_b32 s18, v254, 6
	s_or_b32 s8, s8, s54
	v_readlane_b32 s19, v254, 7
	s_and_b64 s[18:19], s[18:19], exec
	s_cselect_b32 s58, s8, s45
	s_ashr_i32 s18, s58, 6
	s_lshl_b32 s8, s58, 7
	s_ashr_i32 s19, s18, 31
	s_and_b32 s8, s8, 0x780
	s_lshl_b64 s[38:39], s[18:19], 20
	s_lshl_b64 s[40:41], s[18:19], 21
	s_add_u32 s17, s12, s40
	s_addc_u32 s18, s13, s41
	s_lshl_b32 s19, s58, 3
	s_and_b32 s57, s19, 0x180
	s_lshl_b32 s22, s57, 1
	s_add_u32 s17, s17, s22
	s_addc_u32 s19, s18, 0
	s_add_u32 s18, s17, s36
	s_addc_u32 s19, s19, s37
	s_add_u32 s17, s48, s40
	s_addc_u32 s21, s49, s41
	s_add_u32 s20, s17, s22
	s_addc_u32 s21, s21, 0
	s_add_u32 s17, s50, s40
	s_addc_u32 s23, s51, s41
	s_add_u32 s22, s17, s22
	s_addc_u32 s23, s23, 0
	v_lshl_add_u64 v[0:1], s[20:21], 0, v[216:217]
	v_lshl_add_u64 v[2:3], s[20:21], 0, v[220:221]
	v_lshl_add_u64 v[8:9], s[22:23], 0, v[216:217]
	v_lshl_add_u64 v[10:11], s[22:23], 0, v[220:221]
	v_lshl_add_u64 v[0:1], v[0:1], 0, v[218:219]
	v_lshl_add_u64 v[4:5], v[2:3], 0, v[222:223]
	v_lshl_add_u64 v[8:9], v[8:9], 0, v[218:219]
	v_lshl_add_u64 v[12:13], v[10:11], 0, v[222:223]
	global_load_dwordx4 v[0:3], v[0:1], off
	s_nop 0
	global_load_dwordx4 v[4:7], v[4:5], off
	s_nop 0
	global_load_dwordx4 v[8:11], v[8:9], off
	s_nop 0
	global_load_dwordx4 v[12:15], v[12:13], off
	v_or_b32_e32 v16, s8, v233
	v_lshlrev_b32_e32 v192, 10, v16
	v_lshl_add_u64 v[16:17], s[18:19], 0, v[192:193]
	v_mov_b32_e32 v215, v193
	v_lshl_add_u64 v[16:17], v[16:17], 0, v[214:215]
	global_load_dwordx4 v[160:163], v[16:17], off
	global_load_dwordx4 v[164:167], v[16:17], off offset:32
	global_load_dwordx4 v[168:171], v[16:17], off offset:64
	global_load_dwordx4 v[172:175], v[16:17], off offset:96
	v_lshl_add_u64 v[16:17], s[20:21], 0, v[196:197]
	v_lshl_add_u64 v[18:19], s[20:21], 0, v[198:199]
	v_lshl_add_u64 v[16:17], v[16:17], 0, v[218:219]
	v_lshl_add_u64 v[18:19], v[18:19], 0, v[222:223]
	global_load_dwordx4 v[176:179], v[16:17], off
	global_load_dwordx4 v[180:183], v[18:19], off
	v_add_u32_e32 v192, v202, v234
	v_add_u32_e32 v215, v204, v235
	v_add_u32_e32 v243, v206, v234
	v_add_u32_e32 v244, v208, v235
	s_mov_b32 s17, s16
	s_mov_b32 s18, s16
	s_mov_b32 s19, s16
	s_mov_b32 s20, s16
	s_mov_b32 s21, s16
	s_mov_b32 s22, s16
	s_mov_b32 s23, s16
	s_mov_b32 s24, s16
	s_mov_b32 s25, s16
	s_mov_b32 s26, s16
	s_mov_b32 s27, s16
	s_mov_b32 s28, s16
	s_mov_b32 s29, s16
	s_mov_b32 s30, s16
	s_mov_b32 s31, s16
	v_mov_b32_e32 v246, 0
	v_mov_b32_e32 v245, 0xf149f2ca
	s_waitcnt vmcnt(9)
	ds_write_b128 v192, v[0:3]
	s_waitcnt vmcnt(8)
	ds_write_b128 v215, v[4:7]
	s_waitcnt vmcnt(7)
	ds_write_b128 v243, v[8:11] offset:34816
	s_waitcnt vmcnt(6)
	ds_write_b128 v244, v[12:15] offset:34816
	s_waitcnt lgkmcnt(0)
	s_barrier
	ds_read_b128 v[0:3], v240
	ds_read_b128 v[4:7], v240 offset:32
	s_waitcnt vmcnt(5) lgkmcnt(1)
	v_mfma_f32_32x32x16_bf16 v[80:95], v[0:3], v[160:163], 0
	ds_read_b128 v[0:3], v240 offset:8704
	ds_read_b128 v[8:11], v240 offset:8736
	s_waitcnt lgkmcnt(1)
	v_mfma_f32_32x32x16_bf16 v[64:79], v[0:3], v[160:163], 0
	ds_read_b128 v[0:3], v240 offset:64
	s_waitcnt vmcnt(4)
	v_mfma_f32_32x32x16_bf16 v[80:95], v[4:7], v[164:167], v[80:95]
	ds_read_b128 v[4:7], v240 offset:8768
	ds_read_b128 v[16:19], v240 offset:96
	ds_read_b128 v[20:23], v240 offset:8800
	s_waitcnt vmcnt(1)
	ds_write_b128 v241, v[176:179] offset:17408
	s_waitcnt vmcnt(0)
	ds_write_b128 v242, v[180:183] offset:17408
	s_waitcnt lgkmcnt(0)
	s_barrier
	v_mfma_f32_32x32x16_bf16 v[64:79], v[8:11], v[164:167], v[64:79]
	v_mfma_f32_32x32x16_bf16 v[80:95], v[0:3], v[168:171], v[80:95]
	v_mfma_f32_32x32x16_bf16 v[64:79], v[4:7], v[168:171], v[64:79]
	v_mov_b64_e32 v[0:1], s[16:17]
	v_mov_b64_e32 v[2:3], s[18:19]
	v_mov_b64_e32 v[4:5], s[20:21]
	v_mov_b64_e32 v[6:7], s[22:23]
	v_mov_b64_e32 v[8:9], s[24:25]
	v_mov_b64_e32 v[10:11], s[26:27]
	v_mov_b64_e32 v[12:13], s[28:29]
	v_mfma_f32_32x32x16_bf16 v[80:95], v[16:19], v[172:175], v[80:95]
	v_mov_b64_e32 v[14:15], s[30:31]
	s_lshl_b32 s17, s58, 4
	s_and_b32 s17, s17, 0x300
	s_or_b32 s40, s40, s17
	v_mov_b64_e32 v[46:47], v[14:15]
	v_mov_b64_e32 v[62:63], v[14:15]
	v_lshl_add_u64 v[224:225], v[210:211], 0, s[40:41]
	v_mfma_f32_32x32x16_bf16 v[64:79], v[20:23], v[172:175], v[64:79]
	v_mov_b64_e32 v[30:31], v[14:15]
	v_lshl_add_u64 v[226:227], v[212:213], 0, s[40:41]
	s_mov_b64 s[18:19], 0
	v_mov_b64_e32 v[28:29], v[12:13]
	v_mov_b64_e32 v[26:27], v[10:11]
	v_mov_b64_e32 v[24:25], v[8:9]
	v_mov_b64_e32 v[22:23], v[6:7]
	v_mov_b64_e32 v[20:21], v[4:5]
	v_mov_b64_e32 v[18:19], v[2:3]
	v_mov_b64_e32 v[16:17], v[0:1]
	v_mov_b64_e32 v[44:45], v[12:13]
	v_mov_b64_e32 v[42:43], v[10:11]
	v_mov_b64_e32 v[40:41], v[8:9]
	v_mov_b64_e32 v[38:39], v[6:7]
	v_mov_b64_e32 v[36:37], v[4:5]
	v_mov_b64_e32 v[34:35], v[2:3]
	v_mov_b64_e32 v[32:33], v[0:1]
	v_mov_b64_e32 v[60:61], v[12:13]
	v_mov_b64_e32 v[58:59], v[10:11]
	v_mov_b64_e32 v[56:57], v[8:9]
	v_mov_b64_e32 v[54:55], v[6:7]
	v_mov_b64_e32 v[52:53], v[4:5]
	v_mov_b64_e32 v[50:51], v[2:3]
	v_mov_b64_e32 v[48:49], v[0:1]
	v_readfirstlane_b32 s98, v226
	v_readfirstlane_b32 s99, v227
	s_nop 3
	v_subrev_u32_e32 v247, s98, v226
	v_add_u32_e32 v252, 0x8000, v247
	v_add_u32_e32 v253, 0x10000, v247
	v_add_u32_e32 v245, 0x18000, v247
	s_add_u32 s100, s98, 0xbf10000
	s_addc_u32 s101, s99, 0
	s_add_u32 s98, s98, 0xaf20000
	s_addc_u32 s99, s99, 0
	s_mov_b32 s17, 0
